# code placement: the K=1024 and K=2816 GEMM loop heads aligned to 64 bytes
# speedup vs baseline: 1.0028x; 1.0028x over previous
; #define PG8_STAGE(bufoff, gbase, voff) do { _Pragma("unroll") for (int _i = 0; _i < 2; ++_i) \
;         __builtin_amdgcn_global_load_lds((const unsigned*)((const char*)(gbase) + (voff)[_i]), (PG8_LAS unsigned*)(lds + (bufoff) + ldsw + _i * 8192), 16, 0, 0); } while (0)
; #define PG8_LDA(dst, b, h) do { _Pragma("unroll") for (int m = 0; m < 4; ++m) _Pragma("unroll") for (int k = 0; k < 2; ++k) dst[m][k] = *(const PG8_LAS bf16x8*)(lds + PG8_SA(b, h) + aoff + m * 2048 + k * 1024); } while (0)
; #define PG8_LDB(dst, b, h) do { _Pragma("unroll") for (int n = 0; n < 2; ++n) _Pragma("unroll") for (int k = 0; k < 2; ++k) dst[n][k] = *(const PG8_LAS bf16x8*)(lds + PG8_SB(b, h) + boff + n * 2048 + k * 1024); } while (0)
; #define PG8_MMA(ai, bj, At, Bt) do { __builtin_amdgcn_s_setprio(1); _Pragma("unroll") for (int m = 0; m < 4; ++m) _Pragma("unroll") for (int n = 0; n < 2; ++n) _Pragma("unroll") for (int k = 0; k < 2; ++k) \
;         acc[ai][bj][m][n] = __builtin_amdgcn_mfma_f32_16x16x32_bf16(Bt[n][k], At[m][k], acc[ai][bj][m][n], 0, 0, 0); __builtin_amdgcn_s_setprio(0); } while (0)
; #define PG8_WAIT_V(n) asm volatile("s_waitcnt vmcnt(" #n ")" ::: "memory")
; #define PG8_WAIT_L(n) asm volatile("s_waitcnt lgkmcnt(" #n ")" ::: "memory")
; template <class Epi, class Sched, bool ALIGN_EPI = false, bool SP2 = false>
; __device__ __forceinline__ void gemm_phase(PG8_LAS unsigned char* lds, const Gemm g, const Sched& S, const Epi& E, const int wave0) {
;     ...
;             const bool last = (t == nt - 2);
;             const char* a1 = cA + (size_t)(t + 1) * kstep;
;             const char* a2 = last ? nA : cA + (size_t)(t + 2) * kstep; const char* b2 = last ? nB : cB + (size_t)(t + 2) * kstep;
;             const char* a3 = a2 + kstep; const char* b3 = b2 + kstep;
;             if (last && has_next) S.a_ready(nxt);
;             if constexpr (SP2) {
;             PG8_LDB(B0, 0, 0); PG8_LDB(B1, 0, 1); PG8_SCHED; PG8_LDA(At, 0, 0); PG8_STAGE(PG8_SA(1, 1), a1 + hstep, voffA);
;             PG8_WAIT_V(8); PG8_WAIT_L(0); PG8_BAR; PG8_MMA(0, 0, At, B0); PG8_MMA(0, 1, At, B1); PG8_BAR; PG8_SCHED;
;             PG8_LDA(At, 0, 1); PG8_STAGE(PG8_SB(0, 0), b2, voffB); PG8_STAGE(PG8_SB(0, 1), b2 + hstep, voffB); PG8_STAGE(PG8_SA(0, 0), a2, voffA);
;             PG8_WAIT_V(8); PG8_WAIT_L(0); PG8_BAR; PG8_MMA(1, 0, At, B0); PG8_MMA(1, 1, At, B1); PG8_BAR; PG8_SCHED;
.LBB0_1023:
	s_add_u32 s57, s48, 0x100
	s_addc_u32 s58, s49, 0
	s_mov_b32 s59, -2
	s_waitcnt lgkmcnt(0)
	s_add_u32 s8, s10, 0x100
	s_addc_u32 s9, s11, 0
	s_add_i32 s18, 0, 0x10000
	s_cmp_eq_u32 s59, 40
	s_cselect_b32 s51, s45, s9
	s_cselect_b32 s50, s44, s8
	s_cselect_b32 s49, s47, s58
	s_cselect_b32 s48, s46, s57
	s_add_i32 s19, 0, 0x14000
	v_add_u32_e32 v140, s18, v247
	v_add_u32_e32 v156, s19, v247
	ds_read_b128 v[64:67], v140
	ds_read_b128 v[68:71], v140 offset:1024
	ds_read_b128 v[136:139], v140 offset:2048
	ds_read_b128 v[140:143], v140 offset:3072
	ds_read_b128 v[144:147], v156
	ds_read_b128 v[148:151], v156 offset:1024
	ds_read_b128 v[152:155], v156 offset:2048
	ds_read_b128 v[156:159], v156 offset:3072
	s_add_i32 m0, s33, 0xc000
	ds_read_b128 v[160:163], v245
	ds_read_b128 v[164:167], v245 offset:1024
	ds_read_b128 v[168:171], v245 offset:2048
	ds_read_b128 v[172:175], v245 offset:3072
	ds_read_b128 v[176:179], v245 offset:4096
	ds_read_b128 v[180:183], v245 offset:5120
	ds_read_b128 v[184:187], v245 offset:6144
	ds_read_b128 v[188:191], v245 offset:7168
	global_load_lds_dwordx4 v224, s[10:11]
	s_add_i32 m0, s33, 0xe000
	s_nop 0
	global_load_lds_dwordx4 v226, s[10:11]
	s_waitcnt vmcnt(8)
	s_waitcnt lgkmcnt(0)
	s_barrier
	s_setprio 1
	v_mfma_f32_16x16x32_bf16 v[132:135], v[64:67], v[160:163], 0
	v_mfma_f32_16x16x32_bf16 v[128:131], v[136:139], v[160:163], 0
	v_mfma_f32_16x16x32_bf16 v[116:119], v[64:67], v[168:171], 0
	v_mfma_f32_16x16x32_bf16 v[108:111], v[136:139], v[168:171], 0
	v_mfma_f32_16x16x32_bf16 v[100:103], v[64:67], v[176:179], 0
	v_mfma_f32_16x16x32_bf16 v[92:95], v[136:139], v[176:179], 0
	v_mfma_f32_16x16x32_bf16 v[84:87], v[64:67], v[184:187], 0
	v_mfma_f32_16x16x32_bf16 v[76:79], v[136:139], v[184:187], 0
	v_mfma_f32_16x16x32_bf16 v[132:135], v[68:71], v[164:167], v[132:135]
	v_mfma_f32_16x16x32_bf16 v[128:131], v[140:143], v[164:167], v[128:131]
	v_mfma_f32_16x16x32_bf16 v[116:119], v[68:71], v[172:175], v[116:119]
	v_mfma_f32_16x16x32_bf16 v[108:111], v[140:143], v[172:175], v[108:111]
	v_mfma_f32_16x16x32_bf16 v[100:103], v[68:71], v[180:183], v[100:103]
	v_mfma_f32_16x16x32_bf16 v[92:95], v[140:143], v[180:183], v[92:95]
	v_mfma_f32_16x16x32_bf16 v[84:87], v[68:71], v[188:191], v[84:87]
	v_mfma_f32_16x16x32_bf16 v[76:79], v[140:143], v[188:191], v[76:79]
	v_mfma_f32_16x16x32_bf16 v[124:127], v[144:147], v[160:163], 0
	v_mfma_f32_16x16x32_bf16 v[120:123], v[152:155], v[160:163], 0
	v_mfma_f32_16x16x32_bf16 v[112:115], v[144:147], v[168:171], 0
	v_mfma_f32_16x16x32_bf16 v[104:107], v[152:155], v[168:171], 0
	v_mfma_f32_16x16x32_bf16 v[96:99], v[144:147], v[176:179], 0
	v_mfma_f32_16x16x32_bf16 v[88:91], v[152:155], v[176:179], 0
	v_mfma_f32_16x16x32_bf16 v[80:83], v[144:147], v[184:187], 0
	v_mfma_f32_16x16x32_bf16 v[72:75], v[152:155], v[184:187], 0
	v_mfma_f32_16x16x32_bf16 v[124:127], v[148:151], v[164:167], v[124:127]
	v_mfma_f32_16x16x32_bf16 v[120:123], v[156:159], v[164:167], v[120:123]
	v_mfma_f32_16x16x32_bf16 v[112:115], v[148:151], v[172:175], v[112:115]
	v_mfma_f32_16x16x32_bf16 v[104:107], v[156:159], v[172:175], v[104:107]
	v_mfma_f32_16x16x32_bf16 v[96:99], v[148:151], v[180:183], v[96:99]
	v_mfma_f32_16x16x32_bf16 v[88:91], v[156:159], v[180:183], v[88:91]
	v_mfma_f32_16x16x32_bf16 v[80:83], v[148:151], v[188:191], v[80:83]
	v_mfma_f32_16x16x32_bf16 v[72:75], v[156:159], v[188:191], v[72:75]
	s_setprio 0
	s_barrier
	s_add_i32 s10, s18, s95
	s_mov_b32 m0, s10
	ds_read_b128 v[160:163], v245 offset:16384
	ds_read_b128 v[164:167], v245 offset:17408
	ds_read_b128 v[168:171], v245 offset:18432
	ds_read_b128 v[172:175], v245 offset:19456
	ds_read_b128 v[176:179], v245 offset:20480
	ds_read_b128 v[180:183], v245 offset:21504
	ds_read_b128 v[184:187], v245 offset:22528
	ds_read_b128 v[188:191], v245 offset:23552
	global_load_lds_dwordx4 v218, s[48:49]
	s_add_i32 m0, s10, 0x2000
	s_add_u32 s10, s48, 0xb0000
	s_addc_u32 s11, s49, 0
	s_add_i32 s18, s19, s95
	global_load_lds_dwordx4 v222, s[48:49]
	s_mov_b32 m0, s18
	s_nop 0
	global_load_lds_dwordx4 v218, s[10:11]
	s_add_i32 m0, s18, 0x2000
	s_nop 0
	global_load_lds_dwordx4 v222, s[10:11]
	s_mov_b32 m0, s33
	s_nop 0
	global_load_lds_dwordx4 v216, s[50:51]
	s_mov_b32 m0, s82
	s_nop 0
	global_load_lds_dwordx4 v220, s[50:51]
	s_waitcnt vmcnt(8)
	s_waitcnt lgkmcnt(0)
	s_barrier
	s_setprio 1
	v_mfma_f32_16x16x32_bf16 v[60:63], v[64:67], v[160:163], 0
	v_mfma_f32_16x16x32_bf16 v[52:55], v[136:139], v[160:163], 0
	v_mfma_f32_16x16x32_bf16 v[44:47], v[64:67], v[168:171], 0
	v_mfma_f32_16x16x32_bf16 v[36:39], v[136:139], v[168:171], 0
	v_mfma_f32_16x16x32_bf16 v[28:31], v[64:67], v[176:179], 0
	v_mfma_f32_16x16x32_bf16 v[20:23], v[136:139], v[176:179], 0
	v_mfma_f32_16x16x32_bf16 v[12:15], v[64:67], v[184:187], 0
	v_mfma_f32_16x16x32_bf16 v[4:7], v[136:139], v[184:187], 0
	v_mfma_f32_16x16x32_bf16 v[60:63], v[68:71], v[164:167], v[60:63]
	v_mfma_f32_16x16x32_bf16 v[52:55], v[140:143], v[164:167], v[52:55]
	v_mfma_f32_16x16x32_bf16 v[44:47], v[68:71], v[172:175], v[44:47]
	v_mfma_f32_16x16x32_bf16 v[36:39], v[140:143], v[172:175], v[36:39]
	v_mfma_f32_16x16x32_bf16 v[28:31], v[68:71], v[180:183], v[28:31]
	v_mfma_f32_16x16x32_bf16 v[20:23], v[140:143], v[180:183], v[20:23]
	v_mfma_f32_16x16x32_bf16 v[12:15], v[68:71], v[188:191], v[12:15]
	v_mfma_f32_16x16x32_bf16 v[4:7], v[140:143], v[188:191], v[4:7]
	v_mfma_f32_16x16x32_bf16 v[56:59], v[144:147], v[160:163], 0
	v_mfma_f32_16x16x32_bf16 v[48:51], v[152:155], v[160:163], 0
	v_mfma_f32_16x16x32_bf16 v[40:43], v[144:147], v[168:171], 0
	v_mfma_f32_16x16x32_bf16 v[32:35], v[152:155], v[168:171], 0
	v_mfma_f32_16x16x32_bf16 v[24:27], v[144:147], v[176:179], 0
	v_mfma_f32_16x16x32_bf16 v[16:19], v[152:155], v[176:179], 0
	v_mfma_f32_16x16x32_bf16 v[8:11], v[144:147], v[184:187], 0
	v_mfma_f32_16x16x32_bf16 v[0:3], v[152:155], v[184:187], 0
	v_mfma_f32_16x16x32_bf16 v[56:59], v[148:151], v[164:167], v[56:59]
	v_mfma_f32_16x16x32_bf16 v[48:51], v[156:159], v[164:167], v[48:51]
	v_mfma_f32_16x16x32_bf16 v[40:43], v[148:151], v[172:175], v[40:43]
	v_mfma_f32_16x16x32_bf16 v[32:35], v[156:159], v[172:175], v[32:35]
	v_mfma_f32_16x16x32_bf16 v[24:27], v[148:151], v[180:183], v[24:27]
	v_mfma_f32_16x16x32_bf16 v[16:19], v[156:159], v[180:183], v[16:19]
	v_mfma_f32_16x16x32_bf16 v[8:11], v[148:151], v[188:191], v[8:11]
	v_mfma_f32_16x16x32_bf16 v[0:3], v[156:159], v[188:191], v[0:3]
	s_setprio 0
	s_barrier
; #define PG8_STAGE(bufoff, gbase, voff) do { _Pragma("unroll") for (int _i = 0; _i < 2; ++_i) \
;         __builtin_amdgcn_global_load_lds((const unsigned*)((const char*)(gbase) + (voff)[_i]), (PG8_LAS unsigned*)(lds + (bufoff) + ldsw + _i * 8192), 16, 0, 0); } while (0)
; #define PG8_LDA(dst, b, h) do { _Pragma("unroll") for (int m = 0; m < 4; ++m) _Pragma("unroll") for (int k = 0; k < 2; ++k) dst[m][k] = *(const PG8_LAS bf16x8*)(lds + PG8_SA(b, h) + aoff + m * 2048 + k * 1024); } while (0)
; #define PG8_LDB(dst, b, h) do { _Pragma("unroll") for (int n = 0; n < 2; ++n) _Pragma("unroll") for (int k = 0; k < 2; ++k) dst[n][k] = *(const PG8_LAS bf16x8*)(lds + PG8_SB(b, h) + boff + n * 2048 + k * 1024); } while (0)
; #define PG8_MMA(ai, bj, At, Bt) do { __builtin_amdgcn_s_setprio(1); _Pragma("unroll") for (int m = 0; m < 4; ++m) _Pragma("unroll") for (int n = 0; n < 2; ++n) _Pragma("unroll") for (int k = 0; k < 2; ++k) \
;         acc[ai][bj][m][n] = __builtin_amdgcn_mfma_f32_16x16x32_bf16(Bt[n][k], At[m][k], acc[ai][bj][m][n], 0, 0, 0); __builtin_amdgcn_s_setprio(0); } while (0)
; #define PG8_WAIT_V(n) asm volatile("s_waitcnt vmcnt(" #n ")" ::: "memory")
; #define PG8_WAIT_L(n) asm volatile("s_waitcnt lgkmcnt(" #n ")" ::: "memory")
; #define PG8_BAR __builtin_amdgcn_s_barrier()
; #define PG8_SCHED __builtin_amdgcn_sched_barrier(0)
; template <class Epi, class Sched, bool ALIGN_EPI = false, bool SP2 = false>
; __device__ __forceinline__ void gemm_phase(PG8_LAS unsigned char* lds, const Gemm g, const Sched& S, const Epi& E, const int wave0) {
;     ...
;         for (int t = 0; t < nt; t += 2) {
;     ...
;             PG8_LDB(B0, 1, 0); PG8_LDB(B1, 1, 1); PG8_SCHED; PG8_LDA(At, 1, 0); PG8_STAGE(PG8_SA(0, 1), a2 + hstep, voffA);
;             PG8_WAIT_V(8); PG8_WAIT_L(0); PG8_BAR; PG8_MMA(0, 0, At, B0); PG8_MMA(0, 1, At, B1); PG8_BAR; PG8_SCHED;
;             PG8_LDA(At, 1, 1); PG8_STAGE(PG8_SB(1, 0), b3, voffB); PG8_STAGE(PG8_SB(1, 1), b3 + hstep, voffB); PG8_STAGE(PG8_SA(1, 0), a3, voffA);
;             PG8_WAIT_V(8); PG8_WAIT_L(0); PG8_BAR; PG8_MMA(1, 0, At, B0); PG8_MMA(1, 1, At, B1); PG8_BAR; PG8_SCHED;
	s_add_i32 s18, 0, 0x18000
	s_add_i32 s19, 0, 0x1c000
	v_add_u32_e32 v140, s18, v247
	v_add_u32_e32 v156, s19, v247
	ds_read_b128 v[64:67], v140
	ds_read_b128 v[68:71], v140 offset:1024
	ds_read_b128 v[136:139], v140 offset:2048
	ds_read_b128 v[140:143], v140 offset:3072
	ds_read_b128 v[144:147], v156
	ds_read_b128 v[148:151], v156 offset:1024
	ds_read_b128 v[152:155], v156 offset:2048
	ds_read_b128 v[156:159], v156 offset:3072
	s_add_u32 s10, s50, 0xb0000
	s_addc_u32 s11, s51, 0
	s_mov_b32 m0, s16
	ds_read_b128 v[160:163], v245 offset:32768
	ds_read_b128 v[164:167], v245 offset:33792
	ds_read_b128 v[168:171], v245 offset:34816
	ds_read_b128 v[172:175], v245 offset:35840
	ds_read_b128 v[176:179], v245 offset:36864
	ds_read_b128 v[180:183], v245 offset:37888
	ds_read_b128 v[184:187], v245 offset:38912
	ds_read_b128 v[188:191], v245 offset:39936
	global_load_lds_dwordx4 v216, s[10:11]
	s_mov_b32 m0, s83
	s_nop 0
	global_load_lds_dwordx4 v220, s[10:11]
	s_waitcnt vmcnt(8)
	s_waitcnt lgkmcnt(0)
	s_barrier
	s_setprio 1
	v_mfma_f32_16x16x32_bf16 v[132:135], v[64:67], v[160:163], v[132:135]
	v_mfma_f32_16x16x32_bf16 v[128:131], v[136:139], v[160:163], v[128:131]
	v_mfma_f32_16x16x32_bf16 v[116:119], v[64:67], v[168:171], v[116:119]
	v_mfma_f32_16x16x32_bf16 v[108:111], v[136:139], v[168:171], v[108:111]
	v_mfma_f32_16x16x32_bf16 v[100:103], v[64:67], v[176:179], v[100:103]
	v_mfma_f32_16x16x32_bf16 v[92:95], v[136:139], v[176:179], v[92:95]
	v_mfma_f32_16x16x32_bf16 v[84:87], v[64:67], v[184:187], v[84:87]
	v_mfma_f32_16x16x32_bf16 v[76:79], v[136:139], v[184:187], v[76:79]
	v_mfma_f32_16x16x32_bf16 v[132:135], v[68:71], v[164:167], v[132:135]
	v_mfma_f32_16x16x32_bf16 v[128:131], v[140:143], v[164:167], v[128:131]
	v_mfma_f32_16x16x32_bf16 v[116:119], v[68:71], v[172:175], v[116:119]
	v_mfma_f32_16x16x32_bf16 v[108:111], v[140:143], v[172:175], v[108:111]
	v_mfma_f32_16x16x32_bf16 v[100:103], v[68:71], v[180:183], v[100:103]
	v_mfma_f32_16x16x32_bf16 v[92:95], v[140:143], v[180:183], v[92:95]
	v_mfma_f32_16x16x32_bf16 v[84:87], v[68:71], v[188:191], v[84:87]
	v_mfma_f32_16x16x32_bf16 v[76:79], v[140:143], v[188:191], v[76:79]
	v_mfma_f32_16x16x32_bf16 v[124:127], v[144:147], v[160:163], v[124:127]
	v_mfma_f32_16x16x32_bf16 v[120:123], v[152:155], v[160:163], v[120:123]
	v_mfma_f32_16x16x32_bf16 v[112:115], v[144:147], v[168:171], v[112:115]
	v_mfma_f32_16x16x32_bf16 v[104:107], v[152:155], v[168:171], v[104:107]
	v_mfma_f32_16x16x32_bf16 v[96:99], v[144:147], v[176:179], v[96:99]
	v_mfma_f32_16x16x32_bf16 v[88:91], v[152:155], v[176:179], v[88:91]
	v_mfma_f32_16x16x32_bf16 v[80:83], v[144:147], v[184:187], v[80:83]
	v_mfma_f32_16x16x32_bf16 v[72:75], v[152:155], v[184:187], v[72:75]
	v_mfma_f32_16x16x32_bf16 v[124:127], v[148:151], v[164:167], v[124:127]
	v_mfma_f32_16x16x32_bf16 v[120:123], v[156:159], v[164:167], v[120:123]
	v_mfma_f32_16x16x32_bf16 v[112:115], v[148:151], v[172:175], v[112:115]
	v_mfma_f32_16x16x32_bf16 v[104:107], v[156:159], v[172:175], v[104:107]
	v_mfma_f32_16x16x32_bf16 v[96:99], v[148:151], v[180:183], v[96:99]
	v_mfma_f32_16x16x32_bf16 v[88:91], v[156:159], v[180:183], v[88:91]
	v_mfma_f32_16x16x32_bf16 v[80:83], v[148:151], v[188:191], v[80:83]
	v_mfma_f32_16x16x32_bf16 v[72:75], v[156:159], v[188:191], v[72:75]
	s_setprio 0
	s_barrier
	s_add_i32 s10, s18, s95
	s_add_i32 m0, s10, 0xffffff80
	ds_read_b128 v[160:163], v245 offset:49152
	ds_read_b128 v[164:167], v245 offset:50176
	ds_read_b128 v[168:171], v245 offset:51200
	ds_read_b128 v[172:175], v245 offset:52224
	ds_read_b128 v[176:179], v245 offset:53248
	ds_read_b128 v[180:183], v245 offset:54272
	ds_read_b128 v[184:187], v245 offset:55296
	ds_read_b128 v[188:191], v245 offset:56320
	global_load_lds_dwordx4 v218, s[48:49] offset:128
	s_add_i32 m0, s10, 0x1f80
	s_add_u32 s10, s48, 0xb0080
	s_addc_u32 s11, s49, 0
	s_add_i32 s18, s19, s95
	global_load_lds_dwordx4 v222, s[48:49] offset:128
	s_mov_b32 m0, s18
	s_nop 0
	global_load_lds_dwordx4 v218, s[10:11]
	s_add_i32 m0, s18, 0x2000
	s_nop 0
	global_load_lds_dwordx4 v222, s[10:11]
	s_add_i32 m0, s17, 0xffffff80
	s_nop 0
	global_load_lds_dwordx4 v216, s[50:51] offset:128
	s_add_i32 m0, s23, 0xffffff80
	s_nop 0
	global_load_lds_dwordx4 v220, s[50:51] offset:128
	s_waitcnt vmcnt(8)
	s_waitcnt lgkmcnt(0)
	s_barrier
	s_setprio 1
	v_mfma_f32_16x16x32_bf16 v[60:63], v[64:67], v[160:163], v[60:63]
	v_mfma_f32_16x16x32_bf16 v[52:55], v[136:139], v[160:163], v[52:55]
	v_mfma_f32_16x16x32_bf16 v[44:47], v[64:67], v[168:171], v[44:47]
	v_mfma_f32_16x16x32_bf16 v[36:39], v[136:139], v[168:171], v[36:39]
	v_mfma_f32_16x16x32_bf16 v[28:31], v[64:67], v[176:179], v[28:31]
	v_mfma_f32_16x16x32_bf16 v[20:23], v[136:139], v[176:179], v[20:23]
	v_mfma_f32_16x16x32_bf16 v[12:15], v[64:67], v[184:187], v[12:15]
	v_mfma_f32_16x16x32_bf16 v[4:7], v[136:139], v[184:187], v[4:7]
	v_mfma_f32_16x16x32_bf16 v[60:63], v[68:71], v[164:167], v[60:63]
	v_mfma_f32_16x16x32_bf16 v[52:55], v[140:143], v[164:167], v[52:55]
	v_mfma_f32_16x16x32_bf16 v[44:47], v[68:71], v[172:175], v[44:47]
	v_mfma_f32_16x16x32_bf16 v[36:39], v[140:143], v[172:175], v[36:39]
	v_mfma_f32_16x16x32_bf16 v[28:31], v[68:71], v[180:183], v[28:31]
	v_mfma_f32_16x16x32_bf16 v[20:23], v[140:143], v[180:183], v[20:23]
	v_mfma_f32_16x16x32_bf16 v[12:15], v[68:71], v[188:191], v[12:15]
	v_mfma_f32_16x16x32_bf16 v[4:7], v[140:143], v[188:191], v[4:7]
	v_mfma_f32_16x16x32_bf16 v[56:59], v[144:147], v[160:163], v[56:59]
	v_mfma_f32_16x16x32_bf16 v[48:51], v[152:155], v[160:163], v[48:51]
	v_mfma_f32_16x16x32_bf16 v[40:43], v[144:147], v[168:171], v[40:43]
	v_mfma_f32_16x16x32_bf16 v[32:35], v[152:155], v[168:171], v[32:35]
	v_mfma_f32_16x16x32_bf16 v[24:27], v[144:147], v[176:179], v[24:27]
	v_mfma_f32_16x16x32_bf16 v[16:19], v[152:155], v[176:179], v[16:19]
	v_mfma_f32_16x16x32_bf16 v[8:11], v[144:147], v[184:187], v[8:11]
	v_mfma_f32_16x16x32_bf16 v[0:3], v[152:155], v[184:187], v[0:3]
	v_mfma_f32_16x16x32_bf16 v[56:59], v[148:151], v[164:167], v[56:59]
	v_mfma_f32_16x16x32_bf16 v[48:51], v[156:159], v[164:167], v[48:51]
	v_mfma_f32_16x16x32_bf16 v[40:43], v[148:151], v[172:175], v[40:43]
	v_mfma_f32_16x16x32_bf16 v[32:35], v[156:159], v[172:175], v[32:35]
	v_mfma_f32_16x16x32_bf16 v[24:27], v[148:151], v[180:183], v[24:27]
	v_mfma_f32_16x16x32_bf16 v[16:19], v[156:159], v[180:183], v[16:19]
	v_mfma_f32_16x16x32_bf16 v[8:11], v[148:151], v[188:191], v[8:11]
	v_mfma_f32_16x16x32_bf16 v[0:3], v[156:159], v[188:191], v[0:3]
	s_setprio 0
	s_barrier
	s_add_i32 s59, s59, 2
	s_add_u32 s57, s57, 0x100
	s_addc_u32 s58, s58, 0
	s_cmp_gt_u32 s59, 41
	s_mov_b64 s[10:11], s[8:9]
	.p2align	6

; #define PG8_STAGE(bufoff, gbase, voff) do { _Pragma("unroll") for (int _i = 0; _i < 2; ++_i) \
;         __builtin_amdgcn_global_load_lds((const unsigned*)((const char*)(gbase) + (voff)[_i]), (PG8_LAS unsigned*)(lds + (bufoff) + ldsw + _i * 8192), 16, 0, 0); } while (0)
; #define PG8_LDA(dst, b, h) do { _Pragma("unroll") for (int m = 0; m < 4; ++m) _Pragma("unroll") for (int k = 0; k < 2; ++k) dst[m][k] = *(const PG8_LAS bf16x8*)(lds + PG8_SA(b, h) + aoff + m * 2048 + k * 1024); } while (0)
; #define PG8_LDB(dst, b, h) do { _Pragma("unroll") for (int n = 0; n < 2; ++n) _Pragma("unroll") for (int k = 0; k < 2; ++k) dst[n][k] = *(const PG8_LAS bf16x8*)(lds + PG8_SB(b, h) + boff + n * 2048 + k * 1024); } while (0)
; #define PG8_WAIT_V(n) asm volatile("s_waitcnt vmcnt(" #n ")" ::: "memory")
; #define PG8_WAIT_L(n) asm volatile("s_waitcnt lgkmcnt(" #n ")" ::: "memory")
; #define PG8_BAR __builtin_amdgcn_s_barrier()
; #define PG8_SCHED __builtin_amdgcn_sched_barrier(0)
; template <class Epi, class Sched, bool ALIGN_EPI = false, bool SP2 = false>
; __device__ __forceinline__ void gemm_phase(PG8_LAS unsigned char* lds, const Gemm g, const Sched& S, const Epi& E, const int wave0) {
;     ...
;         const char* nA = has_next ? (const char*)g.A + (size_t)nxt.pm * tstep : cA; const char* nB = has_next ? (const char*)g.Bt + (size_t)nxt.pn * tstep : cB;
;         for (int t = 0; t < nt; t += 2) {
;             const bool last = (t == nt - 2);
;             const char* a1 = cA + (size_t)(t + 1) * kstep;
;             const char* a2 = last ? nA : cA + (size_t)(t + 2) * kstep; const char* b2 = last ? nB : cB + (size_t)(t + 2) * kstep;
;             const char* a3 = a2 + kstep; const char* b3 = b2 + kstep;
;             if (last && has_next) S.a_ready(nxt);
;             if constexpr (SP2) {
;             PG8_LDB(B0, 0, 0); PG8_LDB(B1, 0, 1); PG8_SCHED; PG8_LDA(At, 0, 0); PG8_STAGE(PG8_SA(1, 1), a1 + hstep, voffA);
;             PG8_WAIT_V(8); PG8_WAIT_L(0); PG8_BAR; PG8_MMA(0, 0, At, B0); PG8_MMA(0, 1, At, B1); PG8_BAR; PG8_SCHED;
;             PG8_LDA(At, 0, 1); PG8_STAGE(PG8_SB(0, 0), b2, voffB); PG8_STAGE(PG8_SB(0, 1), b2 + hstep, voffB); PG8_STAGE(PG8_SA(0, 0), a2, voffA);
;             PG8_WAIT_V(8); PG8_WAIT_L(0); PG8_BAR; PG8_MMA(1, 0, At, B0); PG8_MMA(1, 1, At, B1); PG8_BAR; PG8_SCHED;
.LBB0_1139:
	s_ashr_i32 s49, s48, 31
	s_lshl_b64 s[18:19], s[48:49], 19
	s_add_u32 s50, s36, s18
	s_addc_u32 s51, s37, s19
	s_and_b64 s[18:19], s[6:7], exec
	s_cselect_b32 s9, s51, s11
	s_cselect_b32 s49, s50, s10
	s_ashr_i32 s47, s46, 31
	s_lshl_b64 s[18:19], s[46:47], 19
	s_add_u32 s52, s38, s18
	s_addc_u32 s53, s39, s19
	s_and_b64 s[18:19], s[6:7], exec
	s_cselect_b32 s47, s53, s57
	s_cselect_b32 s60, s52, s56
	s_add_u32 s10, s10, 0x40080
	s_addc_u32 s11, s11, 0
	s_add_u32 s61, s56, 0x100
	s_addc_u32 s62, s57, 0
	s_mov_b32 s63, -2
	global_load_dwordx4 v[192:195], v215, s[40:41] offset:1024
	global_load_dwordx4 v[196:199], v215, s[40:41] offset:1064
	global_load_dwordx4 v[200:203], v215, s[40:41] offset:1048
	s_waitcnt lgkmcnt(0)
	s_add_u32 s18, s10, 0xfffc0080
	s_addc_u32 s19, s11, -1
	s_add_i32 s64, 0, 0x10000
	s_cmp_eq_u32 s63, 12
	s_cselect_b32 s59, s9, s19
	s_cselect_b32 s58, s49, s18
	s_cselect_b32 s57, s47, s62
	s_cselect_b32 s56, s60, s61
	s_add_i32 s65, 0, 0x14000
	v_add_u32_e32 v140, s64, v247
	v_add_u32_e32 v156, s65, v247
	ds_read_b128 v[64:67], v140
	ds_read_b128 v[68:71], v140 offset:1024
	ds_read_b128 v[136:139], v140 offset:2048
	ds_read_b128 v[140:143], v140 offset:3072
	ds_read_b128 v[144:147], v156
	ds_read_b128 v[148:151], v156 offset:1024
	ds_read_b128 v[152:155], v156 offset:2048
	ds_read_b128 v[156:159], v156 offset:3072
	s_add_i32 m0, s33, 0xc000
	ds_read_b128 v[160:163], v245
	ds_read_b128 v[164:167], v245 offset:1024
	ds_read_b128 v[168:171], v245 offset:2048
	ds_read_b128 v[172:175], v245 offset:3072
	ds_read_b128 v[176:179], v245 offset:4096
	ds_read_b128 v[180:183], v245 offset:5120
	ds_read_b128 v[184:187], v245 offset:6144
	ds_read_b128 v[188:191], v245 offset:7168
	global_load_lds_dwordx4 v224, s[10:11]
	s_add_i32 m0, s33, 0xe000
	s_nop 0
	global_load_lds_dwordx4 v226, s[10:11]
	s_waitcnt vmcnt(8)
	s_waitcnt lgkmcnt(0)
	s_barrier
	s_setprio 1
	v_mfma_f32_16x16x32_bf16 v[132:135], v[64:67], v[160:163], 0
	v_mfma_f32_16x16x32_bf16 v[128:131], v[136:139], v[160:163], 0
	v_mfma_f32_16x16x32_bf16 v[116:119], v[64:67], v[168:171], 0
	v_mfma_f32_16x16x32_bf16 v[108:111], v[136:139], v[168:171], 0
	v_mfma_f32_16x16x32_bf16 v[100:103], v[64:67], v[176:179], 0
	v_mfma_f32_16x16x32_bf16 v[92:95], v[136:139], v[176:179], 0
	v_mfma_f32_16x16x32_bf16 v[84:87], v[64:67], v[184:187], 0
	v_mfma_f32_16x16x32_bf16 v[76:79], v[136:139], v[184:187], 0
	v_mfma_f32_16x16x32_bf16 v[132:135], v[68:71], v[164:167], v[132:135]
	v_mfma_f32_16x16x32_bf16 v[128:131], v[140:143], v[164:167], v[128:131]
	v_mfma_f32_16x16x32_bf16 v[116:119], v[68:71], v[172:175], v[116:119]
	v_mfma_f32_16x16x32_bf16 v[108:111], v[140:143], v[172:175], v[108:111]
	v_mfma_f32_16x16x32_bf16 v[100:103], v[68:71], v[180:183], v[100:103]
	v_mfma_f32_16x16x32_bf16 v[92:95], v[140:143], v[180:183], v[92:95]
	v_mfma_f32_16x16x32_bf16 v[84:87], v[68:71], v[188:191], v[84:87]
	v_mfma_f32_16x16x32_bf16 v[76:79], v[140:143], v[188:191], v[76:79]
	v_mfma_f32_16x16x32_bf16 v[124:127], v[144:147], v[160:163], 0
	v_mfma_f32_16x16x32_bf16 v[120:123], v[152:155], v[160:163], 0
	v_mfma_f32_16x16x32_bf16 v[112:115], v[144:147], v[168:171], 0
	v_mfma_f32_16x16x32_bf16 v[104:107], v[152:155], v[168:171], 0
	v_mfma_f32_16x16x32_bf16 v[96:99], v[144:147], v[176:179], 0
	v_mfma_f32_16x16x32_bf16 v[88:91], v[152:155], v[176:179], 0
	v_mfma_f32_16x16x32_bf16 v[80:83], v[144:147], v[184:187], 0
	v_mfma_f32_16x16x32_bf16 v[72:75], v[152:155], v[184:187], 0
	v_mfma_f32_16x16x32_bf16 v[124:127], v[148:151], v[164:167], v[124:127]
	v_mfma_f32_16x16x32_bf16 v[120:123], v[156:159], v[164:167], v[120:123]
	v_mfma_f32_16x16x32_bf16 v[112:115], v[148:151], v[172:175], v[112:115]
	v_mfma_f32_16x16x32_bf16 v[104:107], v[156:159], v[172:175], v[104:107]
	v_mfma_f32_16x16x32_bf16 v[96:99], v[148:151], v[180:183], v[96:99]
	v_mfma_f32_16x16x32_bf16 v[88:91], v[156:159], v[180:183], v[88:91]
	v_mfma_f32_16x16x32_bf16 v[80:83], v[148:151], v[188:191], v[80:83]
	v_mfma_f32_16x16x32_bf16 v[72:75], v[156:159], v[188:191], v[72:75]
	s_setprio 0
	s_barrier
	s_add_i32 s18, s64, s95
	s_mov_b32 m0, s18
	ds_read_b128 v[160:163], v245 offset:16384
	ds_read_b128 v[164:167], v245 offset:17408
	ds_read_b128 v[168:171], v245 offset:18432
	ds_read_b128 v[172:175], v245 offset:19456
	ds_read_b128 v[176:179], v245 offset:20480
	ds_read_b128 v[180:183], v245 offset:21504
	ds_read_b128 v[184:187], v245 offset:22528
	ds_read_b128 v[188:191], v245 offset:23552
	global_load_lds_dwordx4 v218, s[56:57]
	s_add_i32 m0, s18, 0x2000
	s_add_u32 s18, s56, 0x40000
	s_addc_u32 s19, s57, 0
	s_add_i32 s64, s65, s95
	global_load_lds_dwordx4 v222, s[56:57]
	s_mov_b32 m0, s64
	s_nop 0
	global_load_lds_dwordx4 v218, s[18:19]
	s_add_i32 m0, s64, 0x2000
	s_nop 0
	global_load_lds_dwordx4 v222, s[18:19]
	s_mov_b32 m0, s33
	s_nop 0
	global_load_lds_dwordx4 v216, s[58:59]
	s_mov_b32 m0, s82
	s_nop 0
	global_load_lds_dwordx4 v220, s[58:59]
	s_waitcnt vmcnt(8)
	s_waitcnt lgkmcnt(0)
	s_barrier
; #define PG8_STAGE(bufoff, gbase, voff) do { _Pragma("unroll") for (int _i = 0; _i < 2; ++_i) \
;         __builtin_amdgcn_global_load_lds((const unsigned*)((const char*)(gbase) + (voff)[_i]), (PG8_LAS unsigned*)(lds + (bufoff) + ldsw + _i * 8192), 16, 0, 0); } while (0)
; #define PG8_LDA(dst, b, h) do { _Pragma("unroll") for (int m = 0; m < 4; ++m) _Pragma("unroll") for (int k = 0; k < 2; ++k) dst[m][k] = *(const PG8_LAS bf16x8*)(lds + PG8_SA(b, h) + aoff + m * 2048 + k * 1024); } while (0)
; #define PG8_LDB(dst, b, h) do { _Pragma("unroll") for (int n = 0; n < 2; ++n) _Pragma("unroll") for (int k = 0; k < 2; ++k) dst[n][k] = *(const PG8_LAS bf16x8*)(lds + PG8_SB(b, h) + boff + n * 2048 + k * 1024); } while (0)
; #define PG8_MMA(ai, bj, At, Bt) do { __builtin_amdgcn_s_setprio(1); _Pragma("unroll") for (int m = 0; m < 4; ++m) _Pragma("unroll") for (int n = 0; n < 2; ++n) _Pragma("unroll") for (int k = 0; k < 2; ++k) \
;         acc[ai][bj][m][n] = __builtin_amdgcn_mfma_f32_16x16x32_bf16(Bt[n][k], At[m][k], acc[ai][bj][m][n], 0, 0, 0); __builtin_amdgcn_s_setprio(0); } while (0)
; #define PG8_WAIT_V(n) asm volatile("s_waitcnt vmcnt(" #n ")" ::: "memory")
; #define PG8_WAIT_L(n) asm volatile("s_waitcnt lgkmcnt(" #n ")" ::: "memory")
; #define PG8_BAR __builtin_amdgcn_s_barrier()
; #define PG8_SCHED __builtin_amdgcn_sched_barrier(0)
; template <class Epi, class Sched, bool ALIGN_EPI = false, bool SP2 = false>
; __device__ __forceinline__ void gemm_phase(PG8_LAS unsigned char* lds, const Gemm g, const Sched& S, const Epi& E, const int wave0) {
;     ...
;             PG8_WAIT_V(8); PG8_WAIT_L(0); PG8_BAR; PG8_MMA(1, 0, At, B0); PG8_MMA(1, 1, At, B1); PG8_BAR; PG8_SCHED;
;             PG8_LDB(B0, 1, 0); PG8_LDB(B1, 1, 1); PG8_SCHED; PG8_LDA(At, 1, 0); PG8_STAGE(PG8_SA(0, 1), a2 + hstep, voffA);
;             PG8_WAIT_V(8); PG8_WAIT_L(0); PG8_BAR; PG8_MMA(0, 0, At, B0); PG8_MMA(0, 1, At, B1); PG8_BAR; PG8_SCHED;
	s_setprio 1
	v_mfma_f32_16x16x32_bf16 v[60:63], v[64:67], v[160:163], 0
	v_mfma_f32_16x16x32_bf16 v[52:55], v[136:139], v[160:163], 0
	v_mfma_f32_16x16x32_bf16 v[44:47], v[64:67], v[168:171], 0
	v_mfma_f32_16x16x32_bf16 v[36:39], v[136:139], v[168:171], 0
	v_mfma_f32_16x16x32_bf16 v[28:31], v[64:67], v[176:179], 0
	v_mfma_f32_16x16x32_bf16 v[20:23], v[136:139], v[176:179], 0
	v_mfma_f32_16x16x32_bf16 v[12:15], v[64:67], v[184:187], 0
	v_mfma_f32_16x16x32_bf16 v[4:7], v[136:139], v[184:187], 0
	v_mfma_f32_16x16x32_bf16 v[60:63], v[68:71], v[164:167], v[60:63]
	v_mfma_f32_16x16x32_bf16 v[52:55], v[140:143], v[164:167], v[52:55]
	v_mfma_f32_16x16x32_bf16 v[44:47], v[68:71], v[172:175], v[44:47]
	v_mfma_f32_16x16x32_bf16 v[36:39], v[140:143], v[172:175], v[36:39]
	v_mfma_f32_16x16x32_bf16 v[28:31], v[68:71], v[180:183], v[28:31]
	v_mfma_f32_16x16x32_bf16 v[20:23], v[140:143], v[180:183], v[20:23]
	v_mfma_f32_16x16x32_bf16 v[12:15], v[68:71], v[188:191], v[12:15]
	v_mfma_f32_16x16x32_bf16 v[4:7], v[140:143], v[188:191], v[4:7]
	v_mfma_f32_16x16x32_bf16 v[56:59], v[144:147], v[160:163], 0
	v_mfma_f32_16x16x32_bf16 v[48:51], v[152:155], v[160:163], 0
	v_mfma_f32_16x16x32_bf16 v[40:43], v[144:147], v[168:171], 0
	v_mfma_f32_16x16x32_bf16 v[32:35], v[152:155], v[168:171], 0
	v_mfma_f32_16x16x32_bf16 v[24:27], v[144:147], v[176:179], 0
	v_mfma_f32_16x16x32_bf16 v[16:19], v[152:155], v[176:179], 0
	v_mfma_f32_16x16x32_bf16 v[8:11], v[144:147], v[184:187], 0
	v_mfma_f32_16x16x32_bf16 v[0:3], v[152:155], v[184:187], 0
	v_mfma_f32_16x16x32_bf16 v[56:59], v[148:151], v[164:167], v[56:59]
	v_mfma_f32_16x16x32_bf16 v[48:51], v[156:159], v[164:167], v[48:51]
	v_mfma_f32_16x16x32_bf16 v[40:43], v[148:151], v[172:175], v[40:43]
	v_mfma_f32_16x16x32_bf16 v[32:35], v[156:159], v[172:175], v[32:35]
	v_mfma_f32_16x16x32_bf16 v[24:27], v[148:151], v[180:183], v[24:27]
	v_mfma_f32_16x16x32_bf16 v[16:19], v[156:159], v[180:183], v[16:19]
	v_mfma_f32_16x16x32_bf16 v[8:11], v[148:151], v[188:191], v[8:11]
	v_mfma_f32_16x16x32_bf16 v[0:3], v[156:159], v[188:191], v[0:3]
	s_setprio 0
	s_barrier
	s_add_i32 s64, 0, 0x18000
	s_add_i32 s65, 0, 0x1c000
	v_add_u32_e32 v140, s64, v247
	v_add_u32_e32 v156, s65, v247
	ds_read_b128 v[64:67], v140
	ds_read_b128 v[68:71], v140 offset:1024
	ds_read_b128 v[136:139], v140 offset:2048
	ds_read_b128 v[140:143], v140 offset:3072
	ds_read_b128 v[144:147], v156
	ds_read_b128 v[148:151], v156 offset:1024
	ds_read_b128 v[152:155], v156 offset:2048
	ds_read_b128 v[156:159], v156 offset:3072
	s_add_u32 s18, s58, 0x40000
	s_addc_u32 s19, s59, 0
	s_mov_b32 m0, s16
	ds_read_b128 v[160:163], v245 offset:32768
	ds_read_b128 v[164:167], v245 offset:33792
	ds_read_b128 v[168:171], v245 offset:34816
	ds_read_b128 v[172:175], v245 offset:35840
	ds_read_b128 v[176:179], v245 offset:36864
	ds_read_b128 v[180:183], v245 offset:37888
	ds_read_b128 v[184:187], v245 offset:38912
	ds_read_b128 v[188:191], v245 offset:39936
	global_load_lds_dwordx4 v216, s[18:19]
	s_mov_b32 m0, s83
	s_nop 0
	global_load_lds_dwordx4 v220, s[18:19]
	s_waitcnt vmcnt(8)
	s_waitcnt lgkmcnt(0)
	s_barrier
	s_setprio 1
	v_mfma_f32_16x16x32_bf16 v[132:135], v[64:67], v[160:163], v[132:135]
	v_mfma_f32_16x16x32_bf16 v[128:131], v[136:139], v[160:163], v[128:131]
	v_mfma_f32_16x16x32_bf16 v[116:119], v[64:67], v[168:171], v[116:119]
	v_mfma_f32_16x16x32_bf16 v[108:111], v[136:139], v[168:171], v[108:111]
	v_mfma_f32_16x16x32_bf16 v[100:103], v[64:67], v[176:179], v[100:103]
	v_mfma_f32_16x16x32_bf16 v[92:95], v[136:139], v[176:179], v[92:95]
	v_mfma_f32_16x16x32_bf16 v[84:87], v[64:67], v[184:187], v[84:87]
	v_mfma_f32_16x16x32_bf16 v[76:79], v[136:139], v[184:187], v[76:79]
	v_mfma_f32_16x16x32_bf16 v[132:135], v[68:71], v[164:167], v[132:135]
	v_mfma_f32_16x16x32_bf16 v[128:131], v[140:143], v[164:167], v[128:131]
	v_mfma_f32_16x16x32_bf16 v[116:119], v[68:71], v[172:175], v[116:119]
	v_mfma_f32_16x16x32_bf16 v[108:111], v[140:143], v[172:175], v[108:111]
	v_mfma_f32_16x16x32_bf16 v[100:103], v[68:71], v[180:183], v[100:103]
	v_mfma_f32_16x16x32_bf16 v[92:95], v[140:143], v[180:183], v[92:95]
	v_mfma_f32_16x16x32_bf16 v[84:87], v[68:71], v[188:191], v[84:87]
	v_mfma_f32_16x16x32_bf16 v[76:79], v[140:143], v[188:191], v[76:79]
	v_mfma_f32_16x16x32_bf16 v[124:127], v[144:147], v[160:163], v[124:127]
	v_mfma_f32_16x16x32_bf16 v[120:123], v[152:155], v[160:163], v[120:123]
	v_mfma_f32_16x16x32_bf16 v[112:115], v[144:147], v[168:171], v[112:115]
	v_mfma_f32_16x16x32_bf16 v[104:107], v[152:155], v[168:171], v[104:107]
	v_mfma_f32_16x16x32_bf16 v[96:99], v[144:147], v[176:179], v[96:99]
	v_mfma_f32_16x16x32_bf16 v[88:91], v[152:155], v[176:179], v[88:91]
	v_mfma_f32_16x16x32_bf16 v[80:83], v[144:147], v[184:187], v[80:83]
	v_mfma_f32_16x16x32_bf16 v[72:75], v[152:155], v[184:187], v[72:75]
	v_mfma_f32_16x16x32_bf16 v[124:127], v[148:151], v[164:167], v[124:127]
	v_mfma_f32_16x16x32_bf16 v[120:123], v[156:159], v[164:167], v[120:123]
	v_mfma_f32_16x16x32_bf16 v[112:115], v[148:151], v[172:175], v[112:115]
	v_mfma_f32_16x16x32_bf16 v[104:107], v[156:159], v[172:175], v[104:107]
	v_mfma_f32_16x16x32_bf16 v[96:99], v[148:151], v[180:183], v[96:99]
	v_mfma_f32_16x16x32_bf16 v[88:91], v[156:159], v[180:183], v[88:91]
	v_mfma_f32_16x16x32_bf16 v[80:83], v[148:151], v[188:191], v[80:83]
	v_mfma_f32_16x16x32_bf16 v[72:75], v[156:159], v[188:191], v[72:75]
	s_setprio 0
	s_barrier
; #define PG8_STAGE(bufoff, gbase, voff) do { _Pragma("unroll") for (int _i = 0; _i < 2; ++_i) \
;         __builtin_amdgcn_global_load_lds((const unsigned*)((const char*)(gbase) + (voff)[_i]), (PG8_LAS unsigned*)(lds + (bufoff) + ldsw + _i * 8192), 16, 0, 0); } while (0)
; #define PG8_LDA(dst, b, h) do { _Pragma("unroll") for (int m = 0; m < 4; ++m) _Pragma("unroll") for (int k = 0; k < 2; ++k) dst[m][k] = *(const PG8_LAS bf16x8*)(lds + PG8_SA(b, h) + aoff + m * 2048 + k * 1024); } while (0)
; #define PG8_MMA(ai, bj, At, Bt) do { __builtin_amdgcn_s_setprio(1); _Pragma("unroll") for (int m = 0; m < 4; ++m) _Pragma("unroll") for (int n = 0; n < 2; ++n) _Pragma("unroll") for (int k = 0; k < 2; ++k) \
;         acc[ai][bj][m][n] = __builtin_amdgcn_mfma_f32_16x16x32_bf16(Bt[n][k], At[m][k], acc[ai][bj][m][n], 0, 0, 0); __builtin_amdgcn_s_setprio(0); } while (0)
; #define PG8_WAIT_V(n) asm volatile("s_waitcnt vmcnt(" #n ")" ::: "memory")
; #define PG8_WAIT_L(n) asm volatile("s_waitcnt lgkmcnt(" #n ")" ::: "memory")
; #define PG8_BAR __builtin_amdgcn_s_barrier()
; #define PG8_SCHED __builtin_amdgcn_sched_barrier(0)
; template <class Epi, class Sched, bool ALIGN_EPI = false, bool SP2 = false>
; __device__ __forceinline__ void gemm_phase(PG8_LAS unsigned char* lds, const Gemm g, const Sched& S, const Epi& E, const int wave0) {
;     ...
;         for (int t = 0; t < nt; t += 2) {
;     ...
;             PG8_LDA(At, 1, 1); PG8_STAGE(PG8_SB(1, 0), b3, voffB); PG8_STAGE(PG8_SB(1, 1), b3 + hstep, voffB); PG8_STAGE(PG8_SA(1, 0), a3, voffA);
;             PG8_WAIT_V(8); PG8_WAIT_L(0); PG8_BAR; PG8_MMA(1, 0, At, B0); PG8_MMA(1, 1, At, B1); PG8_BAR; PG8_SCHED;
	s_add_i32 s18, s64, s95
	s_add_i32 m0, s18, 0xffffff80
	ds_read_b128 v[160:163], v245 offset:49152
	ds_read_b128 v[164:167], v245 offset:50176
	ds_read_b128 v[168:171], v245 offset:51200
	ds_read_b128 v[172:175], v245 offset:52224
	ds_read_b128 v[176:179], v245 offset:53248
	ds_read_b128 v[180:183], v245 offset:54272
	ds_read_b128 v[184:187], v245 offset:55296
	ds_read_b128 v[188:191], v245 offset:56320
	global_load_lds_dwordx4 v218, s[56:57] offset:128
	s_add_i32 m0, s18, 0x1f80
	s_add_u32 s18, s56, 0x40080
	s_addc_u32 s19, s57, 0
	global_load_lds_dwordx4 v222, s[56:57] offset:128
	s_add_i32 s56, s65, s95
	s_mov_b32 m0, s56
	s_nop 0
	global_load_lds_dwordx4 v218, s[18:19]
	s_add_i32 m0, s56, 0x2000
	s_nop 0
	global_load_lds_dwordx4 v222, s[18:19]
	s_add_i32 m0, s17, 0xffffff80
	s_nop 0
	global_load_lds_dwordx4 v216, s[58:59] offset:128
	s_add_i32 m0, s23, 0xffffff80
	s_nop 0
	global_load_lds_dwordx4 v220, s[58:59] offset:128
	s_waitcnt vmcnt(8)
	s_waitcnt lgkmcnt(0)
	s_barrier
	s_setprio 1
	v_mfma_f32_16x16x32_bf16 v[60:63], v[64:67], v[160:163], v[60:63]
	v_mfma_f32_16x16x32_bf16 v[52:55], v[136:139], v[160:163], v[52:55]
	v_mfma_f32_16x16x32_bf16 v[44:47], v[64:67], v[168:171], v[44:47]
	v_mfma_f32_16x16x32_bf16 v[36:39], v[136:139], v[168:171], v[36:39]
	v_mfma_f32_16x16x32_bf16 v[28:31], v[64:67], v[176:179], v[28:31]
	v_mfma_f32_16x16x32_bf16 v[20:23], v[136:139], v[176:179], v[20:23]
	v_mfma_f32_16x16x32_bf16 v[12:15], v[64:67], v[184:187], v[12:15]
	v_mfma_f32_16x16x32_bf16 v[4:7], v[136:139], v[184:187], v[4:7]
	v_mfma_f32_16x16x32_bf16 v[60:63], v[68:71], v[164:167], v[60:63]
	v_mfma_f32_16x16x32_bf16 v[52:55], v[140:143], v[164:167], v[52:55]
	v_mfma_f32_16x16x32_bf16 v[44:47], v[68:71], v[172:175], v[44:47]
	v_mfma_f32_16x16x32_bf16 v[36:39], v[140:143], v[172:175], v[36:39]
	v_mfma_f32_16x16x32_bf16 v[28:31], v[68:71], v[180:183], v[28:31]
	v_mfma_f32_16x16x32_bf16 v[20:23], v[140:143], v[180:183], v[20:23]
	v_mfma_f32_16x16x32_bf16 v[12:15], v[68:71], v[188:191], v[12:15]
	v_mfma_f32_16x16x32_bf16 v[4:7], v[140:143], v[188:191], v[4:7]
	v_mfma_f32_16x16x32_bf16 v[56:59], v[144:147], v[160:163], v[56:59]
	v_mfma_f32_16x16x32_bf16 v[48:51], v[152:155], v[160:163], v[48:51]
	v_mfma_f32_16x16x32_bf16 v[40:43], v[144:147], v[168:171], v[40:43]
	v_mfma_f32_16x16x32_bf16 v[32:35], v[152:155], v[168:171], v[32:35]
	v_mfma_f32_16x16x32_bf16 v[24:27], v[144:147], v[176:179], v[24:27]
	v_mfma_f32_16x16x32_bf16 v[16:19], v[152:155], v[176:179], v[16:19]
	v_mfma_f32_16x16x32_bf16 v[8:11], v[144:147], v[184:187], v[8:11]
	v_mfma_f32_16x16x32_bf16 v[0:3], v[152:155], v[184:187], v[0:3]
	v_mfma_f32_16x16x32_bf16 v[56:59], v[148:151], v[164:167], v[56:59]
	v_mfma_f32_16x16x32_bf16 v[48:51], v[156:159], v[164:167], v[48:51]
	v_mfma_f32_16x16x32_bf16 v[40:43], v[148:151], v[172:175], v[40:43]
	v_mfma_f32_16x16x32_bf16 v[32:35], v[156:159], v[172:175], v[32:35]
	v_mfma_f32_16x16x32_bf16 v[24:27], v[148:151], v[180:183], v[24:27]
	v_mfma_f32_16x16x32_bf16 v[16:19], v[156:159], v[180:183], v[16:19]
	v_mfma_f32_16x16x32_bf16 v[8:11], v[148:151], v[188:191], v[8:11]
	v_mfma_f32_16x16x32_bf16 v[0:3], v[156:159], v[188:191], v[0:3]
	s_setprio 0
	s_barrier
	s_add_i32 s63, s63, 2
	s_add_u32 s10, s10, 0x100
	s_addc_u32 s11, s11, 0
	s_add_u32 s61, s61, 0x100
	s_addc_u32 s62, s62, 0
	s_cmp_gt_u32 s63, 13
	.p2align	6
